# k60: k58 with the output-projection epilogue's y stores nt instead of sc1
# baseline (speedup 1.0000x reference)
;     __device__ __forceinline__ void operator()(const f32x4 (&acc)[2][2][4][2], const pg8::Unit& u, int wr, int wc, int fr, int fq) const {
;         const int row0 = u.pm * 256 + wr * 64 + fr, col0 = u.pn * 256 + wc * 32 + fq * 4;
;         const float* gt = mod + (size_t)(row0 >> 13) * 3072 + 2048 + col0;
;         f32x4 gv[2][2];
; #pragma unroll
;         for (int bj = 0; bj < 2; ++bj)
; #pragma unroll
;             for (int n = 0; n < 2; ++n) gv[bj][n] = *(const f32x4*)(gt + bj * 128 + 16 * n);
; #pragma unroll
;         for (int ai = 0; ai < 2; ++ai)
; #pragma unroll
;             for (int mp = 0; mp < 2; ++mp) {
;                 f32x4 xv[2][2][2];
; #pragma unroll
;                 for (int mm = 0; mm < 2; ++mm) { const float* xr = xp + (size_t)(row0 + ai * 128 + (2 * mp + mm) * 16) * DM + col0;
; #pragma unroll
;                     for (int bj = 0; bj < 2; ++bj)
; #pragma unroll
;                         for (int n = 0; n < 2; ++n) xv[mm][bj][n] = *(const f32x4*)(xr + bj * 128 + 16 * n); }
;                 asm volatile("" ::: "memory");
; #pragma unroll
;                 for (int mm = 0; mm < 2; ++mm) { float* yr = yp + (size_t)(row0 + ai * 128 + (2 * mp + mm) * 16) * DM + col0;
; #pragma unroll
;                     for (int bj = 0; bj < 2; ++bj)
; #pragma unroll
;                         for (int n = 0; n < 2; ++n) { const f32x4 yv = xv[mm][bj][n] + gv[bj][n] * acc[ai][bj][2 * mp + mm][n]; const float* yp_ = yr + bj * 128 + 16 * n;
;                             asm volatile("global_store_dwordx4 %0, %1, off sc1" :: "v"(yp_), "v"(yv) : "memory"); } }
.LBB0_1050:
	s_lshl_b32 s25, s34, 8
	s_add_i32 s25, s25, s51
	s_ashr_i32 s27, s25, 13
	s_mul_i32 s38, s27, 0xc00
	s_ashr_i32 s39, s38, 31
	v_lshl_or_b32 v128, s57, 8, v164
	s_lshl_b64 s[38:39], s[38:39], 2
	s_add_u32 s38, s92, s38
	v_ashrrev_i32_e32 v129, 31, v128
	v_or_b32_e32 v200, s25, v162
	s_addc_u32 s39, s93, s39
	v_lshlrev_b64 v[156:157], 2, v[128:129]
	v_ashrrev_i32_e32 v201, 31, v200
	v_lshl_add_u64 v[136:137], s[38:39], 0, v[156:157]
	v_lshl_add_u64 v[158:159], s[36:37], 0, v[156:157]
	v_lshlrev_b64 v[160:161], 12, v[200:201]
	v_or_b32_e32 v140, 16, v200
	v_lshl_add_u64 v[138:139], v[136:137], 0, s[10:11]
	v_lshl_add_u64 v[188:189], v[158:159], 0, v[160:161]
	v_ashrrev_i32_e32 v141, 31, v140
	v_add_co_u32_e32 v136, vcc, s56, v136
	global_load_dwordx4 v[132:135], v[138:139], off offset:64
	global_load_dwordx4 v[128:131], v[138:139], off offset:512
	global_load_dwordx4 v[168:171], v[188:189], off
	global_load_dwordx4 v[172:175], v[188:189], off offset:64
	global_load_dwordx4 v[176:179], v[188:189], off offset:512
	v_lshlrev_b64 v[202:203], 12, v[140:141]
	v_lshl_add_u64 v[196:197], v[158:159], 0, v[202:203]
	v_addc_co_u32_e32 v137, vcc, 0, v137, vcc
	global_load_dwordx4 v[180:183], v[196:197], off offset:64
	global_load_dwordx4 v[184:187], v[196:197], off offset:512
	global_load_dwordx4 v[140:143], v[136:137], off
	s_nop 0
	global_load_dwordx4 v[136:139], v[138:139], off offset:576
	s_nop 0
	global_load_dwordx4 v[188:191], v[188:189], off offset:576
	s_nop 0
	global_load_dwordx4 v[192:195], v[196:197], off
	s_nop 0
	global_load_dwordx4 v[196:199], v[196:197], off offset:576
	v_lshl_add_u64 v[206:207], s[90:91], 0, v[160:161]
	v_lshl_add_u64 v[206:207], v[206:207], 0, v[156:157]
	v_lshl_add_u64 v[210:211], v[206:207], 0, 64
	v_lshl_add_u64 v[212:213], v[206:207], 0, s[12:13]
	v_lshl_add_u64 v[202:203], s[90:91], 0, v[202:203]
	v_lshl_add_u64 v[214:215], v[206:207], 0, s[14:15]
	v_lshl_add_u64 v[202:203], v[202:203], 0, v[156:157]
	v_or_b32_e32 v204, 32, v200
	v_lshl_add_u64 v[216:217], v[202:203], 0, 64
	v_ashrrev_i32_e32 v205, 31, v204
	v_lshl_add_u64 v[218:219], v[202:203], 0, s[12:13]
	v_lshlrev_b64 v[204:205], 12, v[204:205]
	v_lshl_add_u64 v[220:221], v[202:203], 0, s[14:15]
	v_lshl_add_u64 v[208:209], v[158:159], 0, v[204:205]
	s_andn2_b64 vcc, exec, s[0:1]
	s_mov_b64 s[0:1], -1
	s_waitcnt vmcnt(0)
	v_pk_fma_f32 v[126:127], v[126:127], v[134:135], v[174:175]
	v_pk_fma_f32 v[124:125], v[124:125], v[132:133], v[172:173]
	v_pk_fma_f32 v[110:111], v[110:111], v[130:131], v[178:179]
	v_pk_fma_f32 v[122:123], v[122:123], v[142:143], v[170:171]
	v_pk_fma_f32 v[120:121], v[120:121], v[140:141], v[168:169]
	v_pk_fma_f32 v[108:109], v[108:109], v[128:129], v[176:177]
	global_store_dwordx4 v[206:207], v[120:123], off nt
	global_store_dwordx4 v[210:211], v[124:127], off nt
	v_pk_fma_f32 v[106:107], v[106:107], v[138:139], v[190:191]
	global_store_dwordx4 v[212:213], v[108:111], off nt
	v_pk_fma_f32 v[104:105], v[104:105], v[136:137], v[188:189]
	v_pk_fma_f32 v[114:115], v[114:115], v[142:143], v[194:195]
	global_store_dwordx4 v[214:215], v[104:107], off nt
	v_pk_fma_f32 v[112:113], v[112:113], v[140:141], v[192:193]
	v_pk_fma_f32 v[118:119], v[118:119], v[134:135], v[182:183]
	global_store_dwordx4 v[202:203], v[112:115], off nt
	v_pk_fma_f32 v[116:117], v[116:117], v[132:133], v[180:181]
	v_pk_fma_f32 v[102:103], v[102:103], v[130:131], v[186:187]
	global_store_dwordx4 v[216:217], v[116:119], off nt
	v_pk_fma_f32 v[100:101], v[100:101], v[128:129], v[184:185]
	v_pk_fma_f32 v[98:99], v[98:99], v[138:139], v[198:199]
	global_store_dwordx4 v[218:219], v[100:103], off nt
	v_pk_fma_f32 v[96:97], v[96:97], v[136:137], v[196:197]
	v_or_b32_e32 v108, 48, v200
	global_store_dwordx4 v[220:221], v[96:99], off nt
	global_load_dwordx4 v[96:99], v[208:209], off
	global_load_dwordx4 v[100:103], v[208:209], off offset:64
	v_ashrrev_i32_e32 v109, 31, v108
	global_load_dwordx4 v[104:107], v[208:209], off offset:512
	v_lshlrev_b64 v[168:169], 12, v[108:109]
	global_load_dwordx4 v[108:111], v[208:209], off offset:576
	v_lshl_add_u64 v[124:125], v[158:159], 0, v[168:169]
	global_load_dwordx4 v[112:115], v[124:125], off
	global_load_dwordx4 v[116:119], v[124:125], off offset:64
	global_load_dwordx4 v[120:123], v[124:125], off offset:512
	s_nop 0
	global_load_dwordx4 v[124:127], v[124:125], off offset:576
	v_lshl_add_u64 v[172:173], s[90:91], 0, v[204:205]
	v_lshl_add_u64 v[172:173], v[172:173], 0, v[156:157]
	v_lshl_add_u64 v[176:177], v[172:173], 0, 64
	v_lshl_add_u64 v[178:179], v[172:173], 0, s[12:13]
	v_lshl_add_u64 v[168:169], s[90:91], 0, v[168:169]
	v_lshl_add_u64 v[180:181], v[172:173], 0, s[14:15]
	v_lshl_add_u64 v[168:169], v[168:169], 0, v[156:157]
	v_lshl_add_u64 v[182:183], v[168:169], 0, 64
	v_lshl_add_u64 v[184:185], v[168:169], 0, s[12:13]
	v_lshl_add_u64 v[170:171], v[160:161], 0, s[16:17]
	v_lshl_add_u64 v[186:187], v[168:169], 0, s[14:15]
	v_lshl_add_u64 v[174:175], v[158:159], 0, v[170:171]
	s_waitcnt vmcnt(7)
	v_pk_fma_f32 v[94:95], v[94:95], v[142:143], v[98:99]
	v_pk_fma_f32 v[92:93], v[92:93], v[140:141], v[96:97]
	s_waitcnt vmcnt(6)
	v_pk_fma_f32 v[90:91], v[90:91], v[134:135], v[102:103]
	global_store_dwordx4 v[172:173], v[92:95], off nt
	v_pk_fma_f32 v[88:89], v[88:89], v[132:133], v[100:101]
	s_waitcnt vmcnt(5)
	v_pk_fma_f32 v[78:79], v[78:79], v[130:131], v[106:107]
	global_store_dwordx4 v[176:177], v[88:91], off nt
	v_pk_fma_f32 v[76:77], v[76:77], v[128:129], v[104:105]
	s_waitcnt vmcnt(4)
	v_pk_fma_f32 v[74:75], v[74:75], v[138:139], v[110:111]
	global_store_dwordx4 v[178:179], v[76:79], off nt
	v_pk_fma_f32 v[72:73], v[72:73], v[136:137], v[108:109]
	s_waitcnt vmcnt(3)
;     __device__ __forceinline__ void operator()(const f32x4 (&acc)[2][2][4][2], const pg8::Unit& u, int wr, int wc, int fr, int fq) const {
;     ...
;             for (int mp = 0; mp < 2; ++mp) {
;                 f32x4 xv[2][2][2];
; #pragma unroll
;                 for (int mm = 0; mm < 2; ++mm) { const float* xr = xp + (size_t)(row0 + ai * 128 + (2 * mp + mm) * 16) * DM + col0;
; #pragma unroll
;                     for (int bj = 0; bj < 2; ++bj)
; #pragma unroll
;                         for (int n = 0; n < 2; ++n) xv[mm][bj][n] = *(const f32x4*)(xr + bj * 128 + 16 * n); }
;                 asm volatile("" ::: "memory");
; #pragma unroll
;                 for (int mm = 0; mm < 2; ++mm) { float* yr = yp + (size_t)(row0 + ai * 128 + (2 * mp + mm) * 16) * DM + col0;
; #pragma unroll
;                     for (int bj = 0; bj < 2; ++bj)
; #pragma unroll
;                         for (int n = 0; n < 2; ++n) { const f32x4 yv = xv[mm][bj][n] + gv[bj][n] * acc[ai][bj][2 * mp + mm][n]; const float* yp_ = yr + bj * 128 + 16 * n;
;                             asm volatile("global_store_dwordx4 %0, %1, off sc1" :: "v"(yp_), "v"(yv) : "memory"); } }
	v_pk_fma_f32 v[86:87], v[86:87], v[142:143], v[114:115]
	global_store_dwordx4 v[180:181], v[72:75], off nt
	v_pk_fma_f32 v[84:85], v[84:85], v[140:141], v[112:113]
	s_waitcnt vmcnt(2)
	v_pk_fma_f32 v[82:83], v[82:83], v[134:135], v[118:119]
	global_store_dwordx4 v[168:169], v[84:87], off nt
	v_pk_fma_f32 v[80:81], v[80:81], v[132:133], v[116:117]
	s_waitcnt vmcnt(1)
	v_pk_fma_f32 v[70:71], v[70:71], v[130:131], v[122:123]
	global_store_dwordx4 v[182:183], v[80:83], off nt
	v_pk_fma_f32 v[68:69], v[68:69], v[128:129], v[120:121]
	s_waitcnt vmcnt(0)
	v_pk_fma_f32 v[66:67], v[66:67], v[138:139], v[126:127]
	global_store_dwordx4 v[184:185], v[68:71], off nt
	v_pk_fma_f32 v[64:65], v[64:65], v[136:137], v[124:125]
	v_lshl_add_u64 v[96:97], v[160:161], 0, s[18:19]
	global_store_dwordx4 v[186:187], v[64:67], off nt
	global_load_dwordx4 v[64:67], v[174:175], off
	global_load_dwordx4 v[68:71], v[174:175], off offset:64
	global_load_dwordx4 v[72:75], v[174:175], off offset:512
	global_load_dwordx4 v[76:79], v[174:175], off offset:576
	v_lshl_add_u64 v[92:93], v[158:159], 0, v[96:97]
	global_load_dwordx4 v[80:83], v[92:93], off
	global_load_dwordx4 v[84:87], v[92:93], off offset:64
	global_load_dwordx4 v[88:91], v[92:93], off offset:512
	s_nop 0
	global_load_dwordx4 v[92:95], v[92:93], off offset:576
	v_lshl_add_u64 v[100:101], s[90:91], 0, v[170:171]
	v_lshl_add_u64 v[100:101], v[100:101], 0, v[156:157]
	v_lshl_add_u64 v[104:105], v[100:101], 0, 64
	v_lshl_add_u64 v[106:107], v[100:101], 0, s[12:13]
	v_lshl_add_u64 v[96:97], s[90:91], 0, v[96:97]
	v_lshl_add_u64 v[108:109], v[100:101], 0, s[14:15]
	v_lshl_add_u64 v[96:97], v[96:97], 0, v[156:157]
	v_lshl_add_u64 v[110:111], v[96:97], 0, 64
	v_lshl_add_u64 v[112:113], v[96:97], 0, s[12:13]
	v_lshl_add_u64 v[98:99], v[160:161], 0, s[20:21]
	v_lshl_add_u64 v[114:115], v[96:97], 0, s[14:15]
	v_lshl_add_u64 v[102:103], v[158:159], 0, v[98:99]
	s_waitcnt vmcnt(7)
	v_pk_fma_f32 v[62:63], v[62:63], v[142:143], v[66:67]
	v_pk_fma_f32 v[60:61], v[60:61], v[140:141], v[64:65]
	s_waitcnt vmcnt(6)
	v_pk_fma_f32 v[58:59], v[58:59], v[134:135], v[70:71]
	global_store_dwordx4 v[100:101], v[60:63], off nt
	v_pk_fma_f32 v[56:57], v[56:57], v[132:133], v[68:69]
	s_waitcnt vmcnt(5)
	v_pk_fma_f32 v[46:47], v[46:47], v[130:131], v[74:75]
	global_store_dwordx4 v[104:105], v[56:59], off nt
	v_pk_fma_f32 v[44:45], v[44:45], v[128:129], v[72:73]
	s_waitcnt vmcnt(4)
	v_pk_fma_f32 v[42:43], v[42:43], v[138:139], v[78:79]
	global_store_dwordx4 v[106:107], v[44:47], off nt
	v_pk_fma_f32 v[40:41], v[40:41], v[136:137], v[76:77]
	s_waitcnt vmcnt(3)
	v_pk_fma_f32 v[54:55], v[54:55], v[142:143], v[82:83]
	global_store_dwordx4 v[108:109], v[40:43], off nt
	v_pk_fma_f32 v[52:53], v[52:53], v[140:141], v[80:81]
	s_waitcnt vmcnt(2)
	v_pk_fma_f32 v[50:51], v[50:51], v[134:135], v[86:87]
	global_store_dwordx4 v[96:97], v[52:55], off nt
	v_pk_fma_f32 v[48:49], v[48:49], v[132:133], v[84:85]
	s_waitcnt vmcnt(1)
	v_pk_fma_f32 v[38:39], v[38:39], v[130:131], v[90:91]
	global_store_dwordx4 v[110:111], v[48:51], off nt
	v_pk_fma_f32 v[36:37], v[36:37], v[128:129], v[88:89]
	s_waitcnt vmcnt(0)
	v_pk_fma_f32 v[34:35], v[34:35], v[138:139], v[94:95]
	global_store_dwordx4 v[112:113], v[36:39], off nt
	v_pk_fma_f32 v[32:33], v[32:33], v[136:137], v[92:93]
	v_lshl_add_u64 v[64:65], v[160:161], 0, s[22:23]
	global_store_dwordx4 v[114:115], v[32:35], off nt
	global_load_dwordx4 v[32:35], v[102:103], off
	global_load_dwordx4 v[36:39], v[102:103], off offset:64
	global_load_dwordx4 v[40:43], v[102:103], off offset:512
	global_load_dwordx4 v[44:47], v[102:103], off offset:576
	v_lshl_add_u64 v[60:61], v[158:159], 0, v[64:65]
	global_load_dwordx4 v[48:51], v[60:61], off
	global_load_dwordx4 v[52:55], v[60:61], off offset:64
	global_load_dwordx4 v[56:59], v[60:61], off offset:512
	s_nop 0
	global_load_dwordx4 v[60:63], v[60:61], off offset:576
	v_lshl_add_u64 v[66:67], s[90:91], 0, v[98:99]
	v_lshl_add_u64 v[66:67], v[66:67], 0, v[156:157]
	v_lshl_add_u64 v[68:69], v[66:67], 0, 64
	v_lshl_add_u64 v[70:71], v[66:67], 0, s[12:13]
	v_lshl_add_u64 v[64:65], s[90:91], 0, v[64:65]
	v_lshl_add_u64 v[72:73], v[66:67], 0, s[14:15]
	v_lshl_add_u64 v[64:65], v[64:65], 0, v[156:157]
	v_lshl_add_u64 v[74:75], v[64:65], 0, 64
	v_lshl_add_u64 v[76:77], v[64:65], 0, s[12:13]
	v_lshl_add_u64 v[78:79], v[64:65], 0, s[14:15]
	s_waitcnt vmcnt(7)
	v_pk_fma_f32 v[30:31], v[30:31], v[142:143], v[34:35]
	v_pk_fma_f32 v[28:29], v[28:29], v[140:141], v[32:33]
	s_waitcnt vmcnt(6)
	v_pk_fma_f32 v[26:27], v[26:27], v[134:135], v[38:39]
	global_store_dwordx4 v[66:67], v[28:31], off nt
	v_pk_fma_f32 v[24:25], v[24:25], v[132:133], v[36:37]
	s_waitcnt vmcnt(5)
	v_pk_fma_f32 v[14:15], v[14:15], v[130:131], v[42:43]
	global_store_dwordx4 v[68:69], v[24:27], off nt
	v_pk_fma_f32 v[12:13], v[12:13], v[128:129], v[40:41]
	s_waitcnt vmcnt(4)
	v_pk_fma_f32 v[10:11], v[10:11], v[138:139], v[46:47]
	global_store_dwordx4 v[70:71], v[12:15], off nt
	v_pk_fma_f32 v[8:9], v[8:9], v[136:137], v[44:45]
	s_waitcnt vmcnt(3)
	v_pk_fma_f32 v[22:23], v[22:23], v[142:143], v[50:51]
	global_store_dwordx4 v[72:73], v[8:11], off nt
	v_pk_fma_f32 v[20:21], v[20:21], v[140:141], v[48:49]
	s_waitcnt vmcnt(2)
	v_pk_fma_f32 v[18:19], v[18:19], v[134:135], v[54:55]
	global_store_dwordx4 v[64:65], v[20:23], off nt
	v_pk_fma_f32 v[16:17], v[16:17], v[132:133], v[52:53]
	s_waitcnt vmcnt(1)
	v_pk_fma_f32 v[6:7], v[6:7], v[130:131], v[58:59]
	global_store_dwordx4 v[74:75], v[16:19], off nt
	v_pk_fma_f32 v[4:5], v[4:5], v[128:129], v[56:57]
	s_waitcnt vmcnt(0)
	v_pk_fma_f32 v[2:3], v[2:3], v[138:139], v[62:63]
	global_store_dwordx4 v[76:77], v[4:7], off nt
	v_pk_fma_f32 v[0:1], v[0:1], v[136:137], v[60:61]
	s_nop 0
	global_store_dwordx4 v[78:79], v[0:3], off nt
	s_cbranch_vccnz .LBB0_1039
	s_andn2_b64 vcc, exec, s[4:5]
	s_cbranch_vccnz .LBB0_1038
	s_barrier
	s_branch .LBB0_1038
